# P5 K-tile global addresses kept as running pointers (no per-step 64-bit mad/exec select), P3 uniform-branch chain trimmed to s_not
# speedup vs baseline: 1.0049x; 1.0028x over previous
; __device__ __forceinline__ unsigned pk2(float lo, float hi) { f32v2_t v = {lo, hi}; bf16v2_t r = __builtin_convertvector(v, bf16v2_t); return __builtin_bit_cast(unsigned, r); }
; __device__ __forceinline__ f32x16 mfma32(bf16x8 a, bf16x8 b, f32x16 c) { return __builtin_amdgcn_mfma_f32_32x32x16_bf16(a, b, c, 0, 0, 0); }
; template <int MODE>
; __device__ void attn_item(const Params& p, char* lds, int grp  , int b, int h, int qblk, int dry) {
;     ...
;       if (MODE == 0 && more) { lwriteK((kt + 1) & 1); gloadV(kt + 1); }
;       f32v2_t ps2 = {0.f, 0.f}; const f32v2_t m2 = {m, m};
;       const char* vp0 = base + KBYTES + l31 * 144 + hh * 16;
; #pragma unroll
;       for (int sub = 0; sub < 2; ++sub) {
; #pragma unroll
;         for (int r = 0; r < 16; r += 2) {
;           f32v2_t v = (f32v2_t){S[sub][r], S[sub][r + 1]} - m2;
;           v[0] = __builtin_amdgcn_exp2f(v[0]); v[1] = __builtin_amdgcn_exp2f(v[1]);
;           S[sub][r] = v[0]; S[sub][r + 1] = v[1]; ps2 += v;
;         }
; #pragma unroll
;         for (int s = 0; s < 2; ++s) {
;           u32x4 w;
;           w.x = pk2(S[sub][8 * s + 0], S[sub][8 * s + 1]); w.y = pk2(S[sub][8 * s + 2], S[sub][8 * s + 3]);
;           w.z = pk2(S[sub][8 * s + 4], S[sub][8 * s + 5]); w.w = pk2(S[sub][8 * s + 6], S[sub][8 * s + 7]);
;           const bf16x8 pf = __builtin_bit_cast(bf16x8, w);
; #pragma unroll
;           for (int blk = 0; blk < DV / 32; ++blk) {
;             bf16x8 vf = *(const bf16x8*)(vp0 + blk * 32 * 144 + sub * 64 + s * 32);
;             O[blk] = mfma32(vf, pf, O[blk]);
;           }
;         }
;       }
;       l += ps2[0] + ps2[1];
;     }
;     if (more) { if (MODE == 1) lwriteK((kt + 1) & 1); lwriteV((kt + 1) & 1); }
;     __syncthreads();
.LBB0_454:
	s_not_b64 s[44:45], s[0:1]
	v_sub_f32_e32 v80, v80, v168
	v_sub_f32_e32 v81, v81, v168
	v_sub_f32_e32 v82, v82, v168
	v_sub_f32_e32 v83, v83, v168
	v_sub_f32_e32 v84, v84, v168
	v_sub_f32_e32 v85, v85, v168
	v_sub_f32_e32 v86, v86, v168
	v_sub_f32_e32 v87, v87, v168
	v_add3_u32 v216, s27, v195, v182
	v_exp_f32_e32 v80, v80
	v_exp_f32_e32 v81, v81
	v_exp_f32_e32 v82, v82
	v_exp_f32_e32 v83, v83
	v_exp_f32_e32 v84, v84
	v_exp_f32_e32 v85, v85
	v_exp_f32_e32 v86, v86
	v_exp_f32_e32 v87, v87
	ds_read_b128 v[238:241], v216 offset:17408
	ds_read_b128 v[242:245], v216 offset:17440
	v_cvt_pk_bf16_f32 v234, v80, v81
	v_cvt_pk_bf16_f32 v235, v82, v83
	v_cvt_pk_bf16_f32 v236, v84, v85
	v_cvt_pk_bf16_f32 v237, v86, v87
	v_sub_f32_e32 v88, v88, v168
	v_sub_f32_e32 v89, v89, v168
	v_sub_f32_e32 v90, v90, v168
	v_sub_f32_e32 v91, v91, v168
	s_waitcnt lgkmcnt(1)
	v_mfma_f32_32x32x16_bf16 v[32:47], v[238:241], v[234:237], v[32:47]
	ds_read_b128 v[238:241], v216 offset:22016
	v_add_f32_e64 v92, v92, -v168
	v_add_f32_e64 v93, v93, -v168
	v_add_f32_e64 v94, v94, -v168
	v_add_f32_e64 v95, v95, -v168
	v_exp_f32_e32 v88, v88
	v_exp_f32_e32 v89, v89
	v_exp_f32_e32 v90, v90
	v_exp_f32_e32 v91, v91
	s_waitcnt lgkmcnt(0)
	v_mfma_f32_32x32x16_bf16 v[48:63], v[238:241], v[234:237], v[48:63]
	ds_read_b128 v[238:241], v216 offset:26624
	v_exp_f32_e32 v92, v92
	v_exp_f32_e32 v93, v93
	v_exp_f32_e32 v94, v94
	v_exp_f32_e32 v95, v95
	v_sub_f32_e32 v64, v64, v168
	v_sub_f32_e32 v65, v65, v168
	v_sub_f32_e32 v66, v66, v168
	v_sub_f32_e32 v67, v67, v168
	s_waitcnt lgkmcnt(0)
	v_mfma_f32_32x32x16_bf16 v[0:15], v[238:241], v[234:237], v[0:15]
	ds_read_b128 v[238:241], v216 offset:31232
	v_add_f32_e64 v68, v68, -v168
	v_add_f32_e64 v69, v69, -v168
	v_add_f32_e64 v70, v70, -v168
	v_add_f32_e64 v71, v71, -v168
	v_exp_f32_e32 v64, v64
	v_exp_f32_e32 v65, v65
	v_exp_f32_e32 v66, v66
	v_exp_f32_e32 v67, v67
	s_waitcnt lgkmcnt(0)
	v_mfma_f32_32x32x16_bf16 v[16:31], v[238:241], v[234:237], v[16:31]
	ds_read_b128 v[238:241], v216 offset:22048
	v_cvt_pk_bf16_f32 v234, v88, v89
	v_cvt_pk_bf16_f32 v235, v90, v91
	v_cvt_pk_bf16_f32 v236, v92, v93
	v_cvt_pk_bf16_f32 v237, v94, v95
	v_exp_f32_e32 v68, v68
	v_exp_f32_e32 v69, v69
	s_waitcnt lgkmcnt(0)
	v_mfma_f32_32x32x16_bf16 v[48:63], v[238:241], v[234:237], v[48:63]
	ds_read_b128 v[238:241], v216 offset:26656
	v_exp_f32_e32 v70, v70
	v_exp_f32_e32 v71, v71
	v_sub_f32_e32 v72, v72, v168
	v_sub_f32_e32 v73, v73, v168
	v_sub_f32_e32 v74, v74, v168
	v_sub_f32_e32 v75, v75, v168
	v_sub_f32_e32 v76, v76, v168
	v_sub_f32_e32 v77, v77, v168
	v_sub_f32_e32 v78, v78, v168
	v_sub_f32_e32 v79, v79, v168
	s_waitcnt lgkmcnt(0)
	v_mfma_f32_32x32x16_bf16 v[0:15], v[238:241], v[234:237], v[0:15]
	ds_read_b128 v[238:241], v216 offset:31264
	v_exp_f32_e32 v72, v72
	v_exp_f32_e32 v73, v73
	v_exp_f32_e32 v74, v74
	v_exp_f32_e32 v75, v75
	v_exp_f32_e32 v76, v76
	v_exp_f32_e32 v77, v77
	s_waitcnt lgkmcnt(0)
	v_mfma_f32_32x32x16_bf16 v[16:31], v[238:241], v[234:237], v[16:31]
	ds_read_b128 v[238:241], v216 offset:17472
	v_exp_f32_e32 v78, v78
	v_exp_f32_e32 v79, v79
	s_and_b64 vcc, exec, s[44:45]
	v_mfma_f32_32x32x16_bf16 v[32:47], v[242:245], v[234:237], v[32:47]
	ds_read_b128 v[242:245], v216 offset:22080
	v_cvt_pk_bf16_f32 v234, v64, v65
	v_cvt_pk_bf16_f32 v235, v66, v67
	v_cvt_pk_bf16_f32 v236, v68, v69
	v_cvt_pk_bf16_f32 v237, v70, v71
	s_waitcnt lgkmcnt(1)
	s_nop 0
	v_mfma_f32_32x32x16_bf16 v[32:47], v[238:241], v[234:237], v[32:47]
	ds_read_b128 v[238:241], v216 offset:26688
	s_waitcnt lgkmcnt(1)
	v_mfma_f32_32x32x16_bf16 v[48:63], v[242:245], v[234:237], v[48:63]
	ds_read_b128 v[242:245], v216 offset:31296
	s_waitcnt lgkmcnt(1)
	v_mfma_f32_32x32x16_bf16 v[0:15], v[238:241], v[234:237], v[0:15]
	ds_read_b128 v[238:241], v216 offset:17504
	s_waitcnt lgkmcnt(1)
	v_mfma_f32_32x32x16_bf16 v[16:31], v[242:245], v[234:237], v[16:31]
	ds_read_b128 v[242:245], v216 offset:22112
	v_cvt_pk_bf16_f32 v234, v72, v73
	v_cvt_pk_bf16_f32 v235, v74, v75
	v_cvt_pk_bf16_f32 v236, v76, v77
	v_cvt_pk_bf16_f32 v237, v78, v79
	s_waitcnt lgkmcnt(1)
	s_nop 0
	v_mfma_f32_32x32x16_bf16 v[32:47], v[238:241], v[234:237], v[32:47]
	ds_read_b128 v[238:241], v216 offset:26720
	s_waitcnt lgkmcnt(1)
	v_mfma_f32_32x32x16_bf16 v[48:63], v[242:245], v[234:237], v[48:63]
	ds_read_b128 v[216:219], v216 offset:31328
	s_waitcnt lgkmcnt(1)
	v_mfma_f32_32x32x16_bf16 v[0:15], v[238:241], v[234:237], v[0:15]
	s_waitcnt lgkmcnt(0)
	v_mfma_f32_32x32x16_bf16 v[16:31], v[216:219], v[234:237], v[16:31]
	s_cbranch_vccnz .LBB0_458
	s_bitcmp1_b32 s3, 0
	s_cselect_b32 s0, 0x8c00, 0
	v_add3_u32 v217, s0, v174, v175
	s_waitcnt vmcnt(7)
	ds_write_b128 v217, v[112:115]
	v_add3_u32 v217, s0, v176, v175
	s_waitcnt vmcnt(6)
	ds_write_b128 v217, v[116:119]
	v_add3_u32 v217, s0, v177, v175
	s_waitcnt vmcnt(5)
	ds_write_b128 v217, v[120:123]
	v_add3_u32 v217, s0, v178, v175
	s_waitcnt vmcnt(4)
	ds_write_b128 v217, v[124:127]
	v_add3_u32 v216, s0, v179, v187
	v_add3_u32 v217, s0, v190, v187
	v_add3_u32 v218, s0, v191, v187
	v_add3_u32 v219, s0, v192, v187
	s_waitcnt vmcnt(3)
	ds_write_b128 v216, v[128:131] offset:17408
	s_waitcnt vmcnt(2)
	ds_write_b128 v217, v[132:135] offset:17408
	s_waitcnt vmcnt(1)
	ds_write_b128 v218, v[136:139] offset:17408
	s_waitcnt vmcnt(0)
	ds_write_b128 v219, v[140:143] offset:17408

; __device__ void attn_item_mla(const Params& p, char* lds, int grp, int b, int h, int qblk, int dry) {
;     ...
;   u32x4 rk[3], rv[2];
;   auto gload = [&](int kt) {
; #pragma unroll
;     for (int i = 0; i < 3; ++i) {
;       const int q = tid + 256 * i; const int row = q / 12, ch = q % 12;
;       const bf16_t* src = (ch < 8) ? kg + (size_t)(kt * 64 + row) * LDH + ch * 8 : kpe + (size_t)(kt * 64 + row) * 32 + (ch - 8) * 8;
;       rk[i] = *(const u32x4*)src;
;     }
; #pragma unroll
;     for (int i = 0; i < 2; ++i) { const int q = tid + 256 * i; const int row = q >> 3, ch = q & 7; rv[i] = *(const u32x4*)(vg + (size_t)row * Lk + kt * 64 + ch * 8); }
;   };
.LBB0_691:
	s_add_i32 s58, s2, 1
	s_cmp_lt_u32 s58, s23
	s_cselect_b64 s[54:55], -1, 0
	s_cmp_ge_u32 s58, s23
	s_cbranch_scc1 .LBB0_705
	s_lshl_b32 s16, s58, 6
	s_cmp_lg_u32 s2, 0
	s_cbranch_scc1 .Lp5_addr_fast
	v_add_u32_e32 v4, s16, v196
	v_ashrrev_i32_e32 v5, 31, v4
	s_and_saveexec_b64 s[0:1], s[40:41]
	s_xor_b64 s[0:1], exec, s[0:1]
	v_lshlrev_b64 v[222:223], 6, v[4:5]
	v_lshl_add_u64 v[222:223], v[208:209], 0, v[222:223]
	v_lshl_add_u64 v[222:223], v[222:223], 0, s[18:19]
	s_andn2_saveexec_b64 s[0:1], s[0:1]
	v_mad_i64_i32 v[222:223], s[56:57], v4, s34, v[210:211]
	s_or_b64 exec, exec, s[0:1]
	global_load_dwordx4 v[144:147], v[222:223], off
	v_add_u32_e32 v4, s16, v198
	v_ashrrev_i32_e32 v5, 31, v4
	s_and_saveexec_b64 s[0:1], s[42:43]
	s_xor_b64 s[0:1], exec, s[0:1]
	v_lshlrev_b64 v[224:225], 6, v[4:5]
	v_lshl_add_u64 v[224:225], v[212:213], 0, v[224:225]
	v_lshl_add_u64 v[224:225], v[224:225], 0, s[18:19]
	s_andn2_saveexec_b64 s[0:1], s[0:1]
	v_mad_i64_i32 v[224:225], s[56:57], v4, s34, v[214:215]
	s_or_b64 exec, exec, s[0:1]
	global_load_dwordx4 v[148:151], v[224:225], off
	v_add_u32_e32 v4, s16, v200
	v_ashrrev_i32_e32 v5, 31, v4
	s_and_saveexec_b64 s[0:1], s[44:45]
	s_xor_b64 s[0:1], exec, s[0:1]
	v_lshlrev_b64 v[226:227], 6, v[4:5]
	v_lshl_add_u64 v[226:227], v[216:217], 0, v[226:227]
	v_lshl_add_u64 v[226:227], v[226:227], 0, s[18:19]
	s_andn2_saveexec_b64 s[0:1], s[0:1]
	v_mad_i64_i32 v[226:227], s[56:57], v4, s34, v[218:219]
	s_or_b64 exec, exec, s[0:1]
	global_load_dwordx4 v[168:171], v[226:227], off
	s_lshl_b32 s0, s34, 6
	v_mov_b32_e32 v244, s0
	v_mov_b32_e32 v245, 0x1000
	v_cndmask_b32_e64 v228, v244, v245, s[40:41]
	v_cndmask_b32_e64 v230, v244, v245, s[42:43]
	v_cndmask_b32_e64 v232, v244, v245, s[44:45]
	v_mov_b32_e32 v229, 0
	v_mov_b32_e32 v231, 0
	v_mov_b32_e32 v233, 0
	s_branch .Lp5_addr_done
.Lp5_addr_fast:
	v_lshl_add_u64 v[222:223], v[222:223], 0, v[228:229]
	global_load_dwordx4 v[144:147], v[222:223], off
	v_lshl_add_u64 v[224:225], v[224:225], 0, v[230:231]
	global_load_dwordx4 v[148:151], v[224:225], off
	v_lshl_add_u64 v[226:227], v[226:227], 0, v[232:233]
	global_load_dwordx4 v[168:171], v[226:227], off
.Lp5_addr_done:
	s_lshl_b64 s[0:1], s[16:17], 1
	v_lshl_add_u64 v[2:3], v[204:205], 0, s[0:1]
	v_lshl_add_u64 v[4:5], v[206:207], 0, s[0:1]
	global_load_dwordx4 v[172:175], v[2:3], off
	global_load_dwordx4 v[176:179], v[4:5], off

; __device__ __forceinline__ unsigned xb_ld(unsigned* p)              { return __hip_atomic_load(p, __ATOMIC_RELAXED, __HIP_MEMORY_SCOPE_AGENT); }
; __device__ __forceinline__ void grid_barrier(unsigned* bar, unsigned xcc, volatile unsigned* st) {
;   asm volatile("s_waitcnt vmcnt(0)" ::: "memory");
;   __syncthreads();
;   if (threadIdx.x == 0) {
;     __builtin_amdgcn_s_waitcnt(0);
;     unsigned nloc = st[0], nx = st[1];
;     if (nloc == 0u) {
;       const unsigned G = gridDim.x;
;       for (;;) {
;         unsigned sum = 0u, cnt = 0u, mine = 0u;
; #pragma unroll
;         for (unsigned j = 0; j < 16; ++j) { const unsigned c = xb_ld(&bar[XB_XCNT(j)]); sum += c; cnt += (c > 0u) ? 1u : 0u; mine = (j == xcc) ? c : mine; }
;         if (sum == G) { nloc = mine; nx = cnt; break; }
;         __builtin_amdgcn_s_sleep(1);
;       }
;       st[0] = nloc; st[1] = nx;
.LBB0_748:
	v_bfe_u32 v222, v181, 5, 1
	v_and_b32_e32 v223, 64, v181
	v_lshrrev_b32_e32 v224, 1, v181
	v_bfe_u32 v229, v181, 1, 3
	v_bitop3_b32 v225, v222, v229, 2 bitop3:0x36
	v_bitop3_b32 v226, v222, v229, 4 bitop3:0x36
	v_bitop3_b32 v227, v222, v229, 6 bitop3:0x36
	v_lshlrev_b32_e32 v228, 7, v181
	v_bfe_u32 v230, v181, 4, 2
	v_xor_b32_e32 v229, v230, v181
	v_bfe_u32 v230, v181, 3, 3
	v_bfe_u32 v231, v181, 6, 1
	v_lshrrev_b32_e32 v232, 2, v181
	v_lshrrev_b32_e32 v233, 3, v181
	v_readlane_b32 s0, v248, 0
	v_readlane_b32 s1, v248, 1
	s_load_dwordx4 s[24:27], s[0:1], 0xe0
	s_waitcnt lgkmcnt(0)
	s_cmp_gt_i32 s25, 6
	s_cbranch_scc0 .LBB0_780
	s_waitcnt vmcnt(0)
	s_barrier
	s_mov_b64 s[0:1], exec
	v_readlane_b32 s2, v248, 9
	v_readlane_b32 s3, v248, 10
	s_and_b64 s[2:3], s[0:1], s[2:3]
	s_mov_b64 exec, s[2:3]
	s_cbranch_execz .LBB0_779
	s_mov_b64 s[2:3], src_shared_base
	v_mov_b32_e32 v0, 0x12300
	v_mov_b32_e32 v1, s3
	s_waitcnt vmcnt(0) expcnt(0) lgkmcnt(0)
	flat_load_dword v2, v[0:1] sc0 sc1
	s_waitcnt vmcnt(0)
	v_mov_b32_e32 v0, 0x12304
	flat_load_dword v0, v[0:1] sc0 sc1
	s_waitcnt vmcnt(0) lgkmcnt(0)
	v_cmp_eq_u32_e32 vcc, 0, v2
	s_and_saveexec_b64 s[2:3], vcc
	s_cbranch_execz .LBB0_757
	s_load_dword s10, s[10:11], 0x0
	v_mov_b32_e32 v1, 0
	v_mov_b32_e32 v2, 0
	s_branch .LBB0_754
